# small-gemm-first cohort of the out-proj and gate phases chosen by workgroup id bit 7 (was bit 3)
# speedup vs baseline: 1.0215x; 1.0028x over previous
; __device__ __forceinline__ unsigned char* ka_ws() { return (unsigned char*)(GAS unsigned char*)ka_u64(128); }
; __global__ void __launch_bounds__(512, 2) fwd(Args a) {
;     ...
;         if (IN(ph + 2)) {
;     ...
;             unsigned char* ws = ka_ws();
;             pg8::Gemm g{(const bf16_t*)(ws + WS_MIX), (const bf16_t*)(ws + WS_WOUT) + (size_t)L * DM * DM, NPR, DM, DM}; pg8::StaticOrder S; S.init(NPR, DM, G, c);
;             EpiOut E{0};
;             int cb_ = c; asm volatile("" : "+s"(cb_)); const bool small_first = ((cb_ >> 3) & 1) == 0;
; #pragma unroll 1
;             for (int step = 0; step < 2; ++step) {
;                 if ((step == 0) == small_first) small_gemm<EpiOut>(lds, g.A + (size_t)NPR * DM, g.Bt, E, w0);
;                 else pg8::gemm_phase<EpiOut, pg8::StaticOrder, true, true>(lds, g, S, E, w0);
;             }
.LBB0_749:
	s_or_b64 exec, exec, s[4:5]
	s_mov_b64 s[2:3], s[0:1]
	s_waitcnt lgkmcnt(0)
	s_barrier
	s_load_dwordx2 s[4:5], s[2:3], 0x80
	s_mov_b64 s[34:35], -1
	s_waitcnt lgkmcnt(0)
	s_add_u32 s2, s4, 0x9100000
	s_addc_u32 s3, s5, 0
	s_lshl_b32 s6, s96, 20
	s_lshl_b32 s7, s96, 21
	s_add_u32 s7, s4, s7
	s_addc_u32 s8, s5, 0
	s_add_u32 s7, s7, 0x1c00000
	s_addc_u32 s20, s8, 0
	s_mov_b32 s8, s46
	s_bfe_u32 s47, s8, 0x10007
	s_add_u32 s50, s4, 0xb100000
	s_addc_u32 s52, s5, 0
	v_readlane_b32 s4, v255, 14
	v_readlane_b32 s5, v255, 15
	s_add_u32 s10, s7, s4
	s_addc_u32 s11, s20, s5
	s_add_u32 s12, s10, 0x40000
	s_addc_u32 s13, s11, 0
	v_readlane_b32 s4, v255, 12
	v_readlane_b32 s5, v255, 13
	s_add_u32 s14, s2, s4
	s_addc_u32 s15, s3, s5
	s_add_u32 s16, s14, 0x40000
	s_addc_u32 s17, s15, 0
	s_add_u32 s26, s10, 0x40080
	s_addc_u32 s27, s11, 0
	s_mov_b32 s4, 0
	s_branch .LBB0_752

; __device__ __forceinline__ unsigned char* ka_ws() { return (unsigned char*)(GAS unsigned char*)ka_u64(128); }
; __global__ void __launch_bounds__(512, 2) fwd(Args a) {
;     ...
;         if (IN(ph + 3)) {
;     ...
;             unsigned char* ws = ka_ws();
;             pg8::Gemm g{(const bf16_t*)(ws + WS_XB1), (const bf16_t*)(ws + WS_WPG) + (size_t)L * DM * DM, NPR, DM, DM}; pg8::StaticOrder S; S.init(NPR, DM, G, c);
;             EpiGate E{0};
;             int cb_ = c; asm volatile("" : "+s"(cb_)); const bool small_first = ((cb_ >> 3) & 1) == 0;
; #pragma unroll 1
;             for (int step = 0; step < 2; ++step) {
;                 if ((step == 0) == small_first) small_gemm<EpiGate>(lds, g.A + (size_t)NPR * DM, g.Bt, E, w0);
;                 else pg8::gemm_phase<EpiGate, pg8::StaticOrder, true, true>(lds, g, S, E, w0);
;             }
.LBB0_830:
	s_or_b64 exec, exec, s[4:5]
	s_mov_b64 s[2:3], s[0:1]
	s_waitcnt lgkmcnt(0)
	s_barrier
	s_load_dwordx2 s[4:5], s[2:3], 0x80
	s_mov_b32 s8, s46
	s_mov_b64 s[34:35], -1
	s_waitcnt lgkmcnt(0)
	s_add_u32 s2, s4, 0xb200000
	s_addc_u32 s3, s5, 0
	s_lshl_b32 s6, s6, 1
	s_add_u32 s6, s4, s6
	s_addc_u32 s7, s5, 0
	s_add_u32 s6, s6, 0x2400000
	s_addc_u32 s7, s7, 0
	s_bfe_u32 s30, s8, 0x10007
	s_add_u32 s31, s4, 0xd200000
	s_addc_u32 s47, s5, 0
	v_readlane_b32 s4, v255, 14
	v_readlane_b32 s5, v255, 15
	s_add_u32 s10, s6, s4
	s_addc_u32 s11, s7, s5
	s_add_u32 s12, s10, 0x40000
	s_addc_u32 s13, s11, 0
	v_readlane_b32 s4, v255, 12
	v_readlane_b32 s5, v255, 13
	s_add_u32 s14, s2, s4
	s_addc_u32 s15, s3, s5
	s_add_u32 s16, s14, 0x40000
	s_addc_u32 s17, s15, 0
	s_add_u32 s26, s10, 0x40080
	s_addc_u32 s27, s11, 0
	s_mov_b32 s4, 0
	s_branch .LBB0_833
